# phase 0: filter items re-dealt so that the waves carrying two adaLN items take one filter item
# baseline (speedup 1.0000x reference)
.LBB0_54:
	v_writelane_b32 v254, s54, 5
	s_cmpk_gt_i32 s33, 0x11ff
	v_mbcnt_lo_u32_b32 v224, -1, 0
	v_writelane_b32 v254, s55, 6
	s_cbranch_scc1 .LBB0_120
	v_add_u32_e32 v0, -1, v27
	v_and_b32_e32 v0, 15, v0
	v_cvt_f32_ubyte0_e32 v0, v0
	v_mul_f32_e32 v0, 0x416fff97, v0
	s_mov_b32 s4, 0x41700000
	v_div_scale_f32 v1, s[0:1], s4, s4, v0
	v_rcp_f32_e32 v2, v1
	s_mov_b32 s57, 0x437f0000
	s_load_dwordx8 s[16:23], s[30:31], 0x90
	s_load_dwordx4 s[24:27], s[30:31], 0xb0
	v_fma_f32 v3, -v1, v2, 1.0
	v_fmac_f32_e32 v2, v3, v2
	v_div_scale_f32 v3, vcc, v0, s4, v0
	v_mul_f32_e32 v4, v3, v2
	v_fma_f32 v5, -v1, v4, v3
	v_fmac_f32_e32 v4, v5, v2
	v_fma_f32 v1, -v1, v4, v3
	v_div_fmas_f32 v1, v1, v2, v4
	v_div_fixup_f32 v0, v1, s4, v0
	v_cvt_f32_ubyte0_e32 v1, v26
	v_mul_f32_e32 v2, 0x41447cbd, v1
	v_div_scale_f32 v3, s[0:1], s57, s57, v2
	v_rcp_f32_e32 v4, v3
	v_add_f32_e32 v18, 0x38d1b717, v0
	v_mov_b32_e32 v1, 0
	s_add_u32 s2, s28, 0x5100000
	v_fma_f32 v0, -v3, v4, 1.0
	v_fmac_f32_e32 v4, v0, v4
	v_div_scale_f32 v0, vcc, v2, s57, v2
	v_mul_f32_e32 v5, v0, v4
	v_fma_f32 v6, -v3, v5, v0
	v_fmac_f32_e32 v5, v6, v4
	v_fma_f32 v0, -v3, v5, v0
	v_or_b32_e32 v3, 64, v26
	v_cvt_f32_ubyte0_e32 v3, v3
	v_mul_f32_e32 v3, 0x41447cbd, v3
	v_div_scale_f32 v6, s[0:1], s57, s57, v3
	v_rcp_f32_e32 v7, v6
	v_div_fmas_f32 v0, v0, v4, v5
	v_div_fixup_f32 v0, v0, s57, v2
	v_sub_f32_e32 v19, 0xc0447cbd, v0
	v_fma_f32 v0, -v6, v7, 1.0
	v_fmac_f32_e32 v7, v0, v7
	v_div_scale_f32 v0, vcc, v3, s57, v3
	v_mul_f32_e32 v2, v0, v7
	v_fma_f32 v4, -v6, v2, v0
	v_fmac_f32_e32 v2, v4, v7
	v_or_b32_e32 v4, 0x80, v26
	v_cvt_f32_ubyte0_e32 v4, v4
	v_mul_f32_e32 v4, 0x41447cbd, v4
	v_div_scale_f32 v5, s[0:1], s57, s57, v4
	v_fma_f32 v0, -v6, v2, v0
	v_rcp_f32_e32 v6, v5
	v_div_fmas_f32 v0, v0, v7, v2
	v_div_fixup_f32 v0, v0, s57, v3
	v_sub_f32_e32 v20, 0xc0447cbd, v0
	v_fma_f32 v0, -v5, v6, 1.0
	v_fmac_f32_e32 v6, v0, v6
	v_div_scale_f32 v0, vcc, v4, s57, v4
	v_mul_f32_e32 v2, v0, v6
	v_fma_f32 v3, -v5, v2, v0
	v_fmac_f32_e32 v2, v3, v6
	v_or_b32_e32 v3, 0xc0, v26
	v_cvt_f32_ubyte0_e32 v3, v3
	v_mul_f32_e32 v3, 0x41447cbd, v3
	v_fma_f32 v0, -v5, v2, v0
	v_div_scale_f32 v5, s[0:1], s57, s57, v3
	v_rcp_f32_e32 v7, v5
	v_div_fmas_f32 v0, v0, v6, v2
	v_div_fixup_f32 v0, v0, s57, v4
	v_sub_f32_e32 v21, 0xc0447cbd, v0
	v_fma_f32 v0, -v5, v7, 1.0
	v_fmac_f32_e32 v7, v0, v7
	v_div_scale_f32 v0, vcc, v3, s57, v3
	v_mul_f32_e32 v2, v0, v7
	v_fma_f32 v4, -v5, v2, v0
	v_fmac_f32_e32 v2, v4, v7
	v_fma_f32 v0, -v5, v2, v0
	v_div_fmas_f32 v0, v0, v7, v2
	v_div_fixup_f32 v0, v0, s57, v3
	v_sub_f32_e32 v22, 0xc0447cbd, v0
	v_subrev_u32_e32 v0, 33, v26
	s_movk_i32 s0, 0xffdf
	v_cmp_lt_u32_e64 s[6:7], s0, v0
	v_lshlrev_b32_e32 v0, 2, v26
	s_waitcnt lgkmcnt(0)
	v_lshl_add_u64 v[2:3], s[16:17], 0, v[0:1]
	v_lshl_add_u64 v[4:5], s[20:21], 0, v[0:1]
	v_lshl_add_u64 v[6:7], s[24:25], 0, v[0:1]
	s_mov_b64 s[0:1], 0xa00
	v_mbcnt_hi_u32_b32 v0, -1, v224
	v_lshl_add_u64 v[2:3], v[2:3], 0, s[0:1]
	s_mov_b64 s[0:1], 0x700
	v_lshlrev_b32_e32 v32, 2, v0
	s_addc_u32 s56, s29, 0
	s_mov_b32 s35, 0
	v_cmp_eq_u32_e64 s[8:9], 0, v26
	v_cmp_lt_u32_e64 s[4:5], 16, v26
	v_lshl_add_u64 v[4:5], v[4:5], 0, s[0:1]
	s_mov_b32 s61, 0x44ffe000
	s_brev_b32 s62, 18
	s_mov_b32 s63, 0xfe5163ab
	s_mov_b32 s64, 0x3c439041
	s_mov_b32 s65, 0xdb629599
	s_mov_b32 s66, 0xf534ddc0
	s_mov_b32 s67, 0xfc2757d1
	s_mov_b32 s73, 0x4e441529
	s_mov_b32 s69, 0xa2f9836e
	s_mov_b32 s70, 0x3fc90fda
	s_mov_b32 s71, 0x3f22f983
	s_mov_b32 s72, 0xbfc90fda
	v_mov_b32_e32 v23, 0x3c0881c4
	v_mov_b32_e32 v25, 0xbab64f3b
	s_brev_b32 s74, 1
	s_mov_b32 s75, 0x7f800000
	s_mov_b64 s[20:21], 0xb00
	s_movk_i32 s76, 0x1f8
	s_mov_b64 s[24:25], 0x800
	s_movk_i32 s77, 0x1000
	s_mov_b32 s78, 0x3fb8aa3b
	s_mov_b32 s79, 0xc2ce8ed0
	s_mov_b32 s80, 0x42b17218
	s_mov_b64 s[36:37], 0x40000
	s_mov_b32 s81, 0x40000
	v_not_b32_e32 v28, 63
	v_not_b32_e32 v29, 31
	v_mov_b32_e32 v30, 0xffc00000
	v_mov_b32_e32 v31, 0x7fc00000
	v_and_b32_e32 v33, 0x100, v32
	v_mov_b32_e32 v34, 0x7f800000
	s_mov_b32 s101, -1
	s_mov_b32 s100, s33
	s_branch .LBB0_57
.LBB0_56:
	s_cmpk_lg_i32 s68, 0x800
	s_cbranch_scc1 .Lfd_generic
	s_sub_i32 s0, s33, s100
	s_cmp_lg_u32 s0, 0
	s_cbranch_scc1 .Lfd_not_first
	s_movk_i32 s33, 0x7fff
	s_cmpk_lt_u32 s100, 0x100
	s_cbranch_scc1 .Lflt_chk
	s_add_i32 s33, s100, 0x700
	s_cmpk_lt_u32 s100, 0x200
	s_cbranch_scc1 .Lflt_chk
	s_add_i32 s33, s100, 0x800
	s_branch .Lflt_chk
.Lfd_not_first:
	s_cmpk_lg_u32 s0, 0x700
	s_cbranch_scc1 .Lfd_not_second
	s_add_i32 s33, s100, 0x800
	s_branch .Lflt_chk
.Lfd_not_second:
	s_movk_i32 s33, 0x7fff
	s_cmpk_lg_u32 s0, 0x800
	s_cbranch_scc1 .Lflt_chk
	s_cmpk_lt_u32 s100, 0x600
	s_cbranch_scc1 .Lflt_chk
	s_sub_i32 s33, 0x17ff, s100
	s_branch .Lflt_chk
.Lfd_generic:
	s_add_i32 s33, s33, s68
.Lflt_chk:
	s_cmpk_gt_i32 s33, 0x11ff
	s_cbranch_scc1 .LBB0_120
